# indexer threshold search: branch-free per-lane decision logic (lean SALU masks) on top of tile interleave, count loop, mask build, gather search DPP
# speedup vs baseline: 1.0083x; 1.0042x over previous
.LBB0_1533:
	s_nop 1
	v_add_u32_dpp v7, v7, v7 quad_perm:[1,0,3,2] row_mask:0xf bank_mask:0xf bound_ctrl:1
	s_nop 1
	v_add_u32_dpp v7, v7, v7 quad_perm:[2,3,0,1] row_mask:0xf bank_mask:0xf bound_ctrl:1
	s_nop 1
	v_add_u32_dpp v7, v7, v7 row_half_mirror row_mask:0xf bank_mask:0xf bound_ctrl:1
	s_nop 1
	v_add_u32_dpp v7, v7, v7 row_mirror row_mask:0xf bank_mask:0xf bound_ctrl:1
	s_nop 1
	v_add_u32_dpp v7, v7, v7 row_bcast:15 row_mask:0xa bank_mask:0xf
	s_nop 0
	v_readlane_b32 s50, v7, 31
	v_readlane_b32 s51, v7, 63
	s_nop 1
	v_mov_b32_e32 v7, s51
	v_mov_b32_e32 v8, s50
	v_cndmask_b32_e64 v8, v7, v8, s[6:7]
	v_cmp_lt_i32_e64 s[82:83], s33, v8
	v_cmp_eq_u32_e64 s[84:85], s33, v8
	v_cvt_f32_i32_e32 v8, v8
	s_andn2_b64 s[84:85], s[84:85], s[72:73]
	s_nop 0
	v_cndmask_b32_e64 v6, v6, v0, s[84:85]
	s_or_b64 s[84:85], s[84:85], s[72:73]
	s_andn2_b64 s[86:87], s[82:83], s[84:85]
	s_or_b64 s[88:89], s[82:83], s[84:85]
	s_andn2_b64 s[88:89], exec, s[88:89]
	v_cndmask_b32_e64 v4, v4, v0, s[86:87]
	v_cndmask_b32_e64 v3, v3, v8, s[86:87]
	v_cndmask_b32_e64 v5, v5, v0, s[88:89]
	v_cndmask_b32_e64 v2, v2, v8, s[88:89]
	s_or_b64 s[78:79], s[78:79], s[86:87]
	s_or_b64 s[76:77], s[76:77], s[88:89]
	s_and_b64 s[90:91], s[78:79], s[76:77]
	v_sub_f32_e32 v9, v3, v2
	v_rcp_f32_e32 v9, v9
	v_add_f32_e32 v10, 0xc3800000, v3
	s_and_b32 s98, s58, 3
	s_cmp_lg_u32 s98, 3
	s_cselect_b64 vcc, -1, 0
	v_mul_f32_e32 v9, v10, v9
	v_max_f32_e32 v9, 0x3ca3d70a, v9
	v_min_f32_e32 v9, 0x3f7ae148, v9
	v_cndmask_b32_e32 v9, 0.5, v9, vcc
	v_sub_f32_e32 v10, v5, v4
	v_fma_f32 v10, v10, v9, v4
	v_mul_f32_e32 v11, 0.5, v5
	v_fmac_f32_e32 v11, 0.5, v4
	v_cmp_ngt_f32_e32 vcc, v10, v4
	v_cmp_nlt_f32_e64 s[98:99], v10, v5
	v_cmp_ngt_f32_e64 s[100:101], v11, v4
	s_or_b64 s[98:99], vcc, s[98:99]
	v_cmp_nlt_f32_e32 vcc, v11, v5
	s_nop 0
	v_cndmask_b32_e64 v10, v10, v11, s[98:99]
	s_or_b64 s[100:101], vcc, s[100:101]
	s_and_b64 s[100:101], s[100:101], s[98:99]
	s_and_b64 s[100:101], s[100:101], s[90:91]
	s_andn2_b64 s[100:101], s[100:101], s[84:85]
	v_cndmask_b32_e64 v11, -v1, v1, s[82:83]
	v_add_f32_e32 v11, v0, v11
	v_cndmask_b32_e64 v10, v11, v10, s[90:91]
	v_add_f32_e32 v11, v1, v1
	s_or_b64 s[98:99], s[90:91], s[84:85]
	s_andn2_b64 s[98:99], exec, s[98:99]
	v_cndmask_b32_e64 v1, v1, v11, s[98:99]
	v_cndmask_b32_e64 v6, v6, v4, s[100:101]
	s_or_b64 s[72:73], s[84:85], s[100:101]
	s_andn2_b64 s[98:99], exec, s[72:73]
	v_cndmask_b32_e64 v0, v0, v10, s[98:99]
	s_cmp_eq_u64 s[98:99], 0
	s_cbranch_scc1 .Ldx0
	s_cmp_eq_u32 s58, 63
	s_cbranch_scc1 .Ldx0
	s_add_i32 s58, s58, 1
	s_branch .LBB0_1521
.Ldx0:
	s_mov_b64 s[74:75], s[78:79]

.LBB0_2136:
	s_nop 1
	v_add_u32_dpp v7, v7, v7 quad_perm:[1,0,3,2] row_mask:0xf bank_mask:0xf bound_ctrl:1
	s_nop 1
	v_add_u32_dpp v7, v7, v7 quad_perm:[2,3,0,1] row_mask:0xf bank_mask:0xf bound_ctrl:1
	s_nop 1
	v_add_u32_dpp v7, v7, v7 row_half_mirror row_mask:0xf bank_mask:0xf bound_ctrl:1
	s_nop 1
	v_add_u32_dpp v7, v7, v7 row_mirror row_mask:0xf bank_mask:0xf bound_ctrl:1
	s_nop 1
	v_add_u32_dpp v7, v7, v7 row_bcast:15 row_mask:0xa bank_mask:0xf
	s_nop 0
	v_readlane_b32 s0, v7, 31
	v_readlane_b32 s1, v7, 63
	s_nop 1
	v_mov_b32_e32 v7, s1
	v_mov_b32_e32 v8, s0
	v_cndmask_b32_e64 v8, v7, v8, s[8:9]
	v_cmp_lt_i32_e64 s[82:83], s33, v8
	v_cmp_eq_u32_e64 s[84:85], s33, v8
	v_cvt_f32_i32_e32 v8, v8
	s_andn2_b64 s[84:85], s[84:85], s[74:75]
	s_nop 0
	v_cndmask_b32_e64 v6, v6, v0, s[84:85]
	s_or_b64 s[84:85], s[84:85], s[74:75]
	s_andn2_b64 s[86:87], s[82:83], s[84:85]
	s_or_b64 s[88:89], s[82:83], s[84:85]
	s_andn2_b64 s[88:89], exec, s[88:89]
	v_cndmask_b32_e64 v4, v4, v0, s[86:87]
	v_cndmask_b32_e64 v3, v3, v8, s[86:87]
	v_cndmask_b32_e64 v5, v5, v0, s[88:89]
	v_cndmask_b32_e64 v2, v2, v8, s[88:89]
	s_or_b64 s[80:81], s[80:81], s[86:87]
	s_or_b64 s[78:79], s[78:79], s[88:89]
	s_and_b64 s[90:91], s[80:81], s[78:79]
	v_sub_f32_e32 v9, v3, v2
	v_rcp_f32_e32 v9, v9
	v_add_f32_e32 v10, 0xc3800000, v3
	s_and_b32 s98, s60, 3
	s_cmp_lg_u32 s98, 3
	s_cselect_b64 vcc, -1, 0
	v_mul_f32_e32 v9, v10, v9
	v_max_f32_e32 v9, 0x3ca3d70a, v9
	v_min_f32_e32 v9, 0x3f7ae148, v9
	v_cndmask_b32_e32 v9, 0.5, v9, vcc
	v_sub_f32_e32 v10, v5, v4
	v_fma_f32 v10, v10, v9, v4
	v_mul_f32_e32 v11, 0.5, v5
	v_fmac_f32_e32 v11, 0.5, v4
	v_cmp_ngt_f32_e32 vcc, v10, v4
	v_cmp_nlt_f32_e64 s[98:99], v10, v5
	v_cmp_ngt_f32_e64 s[100:101], v11, v4
	s_or_b64 s[98:99], vcc, s[98:99]
	v_cmp_nlt_f32_e32 vcc, v11, v5
	s_nop 0
	v_cndmask_b32_e64 v10, v10, v11, s[98:99]
	s_or_b64 s[100:101], vcc, s[100:101]
	s_and_b64 s[100:101], s[100:101], s[98:99]
	s_and_b64 s[100:101], s[100:101], s[90:91]
	s_andn2_b64 s[100:101], s[100:101], s[84:85]
	v_cndmask_b32_e64 v11, -v1, v1, s[82:83]
	v_add_f32_e32 v11, v0, v11
	v_cndmask_b32_e64 v10, v11, v10, s[90:91]
	v_add_f32_e32 v11, v1, v1
	s_or_b64 s[98:99], s[90:91], s[84:85]
	s_andn2_b64 s[98:99], exec, s[98:99]
	v_cndmask_b32_e64 v1, v1, v11, s[98:99]
	v_cndmask_b32_e64 v6, v6, v4, s[100:101]
	s_or_b64 s[74:75], s[84:85], s[100:101]
	s_andn2_b64 s[98:99], exec, s[74:75]
	v_cndmask_b32_e64 v0, v0, v10, s[98:99]
	s_cmp_eq_u64 s[98:99], 0
	s_cbranch_scc1 .Ldx1
	s_cmp_eq_u32 s60, 63
	s_cbranch_scc1 .Ldx1
	s_add_i32 s60, s60, 1
	s_branch .LBB0_2124
.Ldx1:
	s_mov_b64 s[76:77], s[80:81]

.LBB0_2339:
	s_and_b32 s20, s30, 8
	s_lshl_b32 s20, s20, 2
	s_add_i32 s42, s20, 0
	v_cmp_ge_f32_e64 s[98:99], v19, v0
	v_cmp_ge_f32_e64 s[100:101], v18, v0
	v_cmp_ge_f32_e32 vcc, v17, v0
	v_cndmask_b32_e64 v24, 0, 1, s[98:99]
	v_cmp_ge_f32_e64 s[98:99], v16, v0
	v_addc_co_u32_e64 v24, s[20:21], 0, v24, s[100:101]
	v_cmp_ge_f32_e64 s[100:101], v15, v0
	v_addc_co_u32_e64 v24, s[20:21], 0, v24, vcc
	v_cmp_ge_f32_e32 vcc, v14, v0
	v_addc_co_u32_e64 v24, s[20:21], 0, v24, s[98:99]
	v_cmp_ge_f32_e64 s[98:99], v13, v0
	v_addc_co_u32_e64 v24, s[20:21], 0, v24, s[100:101]
	v_cmp_ge_f32_e64 s[100:101], v12, v0
	v_addc_co_u32_e64 v24, s[20:21], 0, v24, vcc
	v_cmp_ge_f32_e32 vcc, v11, v0
	v_addc_co_u32_e64 v24, s[20:21], 0, v24, s[98:99]
	v_cmp_ge_f32_e64 s[98:99], v10, v0
	v_addc_co_u32_e64 v24, s[20:21], 0, v24, s[100:101]
	v_cmp_ge_f32_e64 s[100:101], v9, v0
	v_addc_co_u32_e64 v24, s[20:21], 0, v24, vcc
	v_cmp_ge_f32_e32 vcc, v8, v0
	v_addc_co_u32_e64 v24, s[20:21], 0, v24, s[98:99]
	v_cmp_ge_f32_e64 s[98:99], v7, v0
	v_addc_co_u32_e64 v24, s[20:21], 0, v24, s[100:101]
	v_cmp_ge_f32_e64 s[100:101], v6, v0
	v_addc_co_u32_e64 v24, s[20:21], 0, v24, vcc
	v_cmp_ge_f32_e32 vcc, v5, v0
	v_addc_co_u32_e64 v24, s[20:21], 0, v24, s[98:99]
	v_cmp_ge_f32_e64 s[98:99], v4, v0
	v_addc_co_u32_e64 v24, s[20:21], 0, v24, s[100:101]
	v_cmp_ge_f32_e64 s[100:101], v20, v0
	v_addc_co_u32_e64 v24, s[20:21], 0, v24, vcc
	v_addc_co_u32_e64 v24, s[20:21], 0, v24, s[98:99]
	v_addc_co_u32_e64 v24, s[20:21], 0, v24, s[100:101]
	v_cvt_f32_u32_e32 v24, v24
	s_nop 1
	v_add_f32_dpp v24, v24, v24 quad_perm:[1,0,3,2] row_mask:0xf bank_mask:0xf bound_ctrl:1
	s_nop 1
	v_add_f32_dpp v24, v24, v24 quad_perm:[2,3,0,1] row_mask:0xf bank_mask:0xf bound_ctrl:1
	s_nop 1
	v_add_f32_dpp v24, v24, v24 row_half_mirror row_mask:0xf bank_mask:0xf bound_ctrl:1
	s_nop 1
	v_add_f32_dpp v24, v24, v24 row_mirror row_mask:0xf bank_mask:0xf bound_ctrl:1
	s_nop 0
	v_readlane_b32 s98, v24, 16
	v_readlane_b32 s99, v24, 32
	v_readlane_b32 s100, v24, 48
	s_nop 1
	v_add_f32_e32 v24, s98, v24
	v_add_f32_e32 v24, s99, v24
	v_mov_b32_e32 v25, s100
	s_and_saveexec_b64 s[20:21], s[0:1]
	s_cbranch_execz .LBB0_2341
	s_lshl_b32 s43, s55, 2
	s_add_i32 s43, s42, s43
	s_waitcnt lgkmcnt(0)
	v_add_f32_e32 v24, v24, v25
	v_mov_b32_e32 v25, s43
	ds_write_b32 v25, v24 offset:64

.LBB0_2710:
	s_and_b32 s20, s30, 8
	s_lshl_b32 s20, s20, 2
	s_add_i32 s42, s20, 0
	v_cmp_ge_f32_e64 s[98:99], v19, v0
	v_cmp_ge_f32_e64 s[100:101], v18, v0
	v_cmp_ge_f32_e32 vcc, v17, v0
	v_cndmask_b32_e64 v24, 0, 1, s[98:99]
	v_cmp_ge_f32_e64 s[98:99], v16, v0
	v_addc_co_u32_e64 v24, s[20:21], 0, v24, s[100:101]
	v_cmp_ge_f32_e64 s[100:101], v15, v0
	v_addc_co_u32_e64 v24, s[20:21], 0, v24, vcc
	v_cmp_ge_f32_e32 vcc, v14, v0
	v_addc_co_u32_e64 v24, s[20:21], 0, v24, s[98:99]
	v_cmp_ge_f32_e64 s[98:99], v13, v0
	v_addc_co_u32_e64 v24, s[20:21], 0, v24, s[100:101]
	v_cmp_ge_f32_e64 s[100:101], v12, v0
	v_addc_co_u32_e64 v24, s[20:21], 0, v24, vcc
	v_cmp_ge_f32_e32 vcc, v11, v0
	v_addc_co_u32_e64 v24, s[20:21], 0, v24, s[98:99]
	v_cmp_ge_f32_e64 s[98:99], v10, v0
	v_addc_co_u32_e64 v24, s[20:21], 0, v24, s[100:101]
	v_cmp_ge_f32_e64 s[100:101], v9, v0
	v_addc_co_u32_e64 v24, s[20:21], 0, v24, vcc
	v_cmp_ge_f32_e32 vcc, v8, v0
	v_addc_co_u32_e64 v24, s[20:21], 0, v24, s[98:99]
	v_cmp_ge_f32_e64 s[98:99], v7, v0
	v_addc_co_u32_e64 v24, s[20:21], 0, v24, s[100:101]
	v_cmp_ge_f32_e64 s[100:101], v6, v0
	v_addc_co_u32_e64 v24, s[20:21], 0, v24, vcc
	v_cmp_ge_f32_e32 vcc, v5, v0
	v_addc_co_u32_e64 v24, s[20:21], 0, v24, s[98:99]
	v_cmp_ge_f32_e64 s[98:99], v4, v0
	v_addc_co_u32_e64 v24, s[20:21], 0, v24, s[100:101]
	v_cmp_ge_f32_e64 s[100:101], v20, v0
	v_addc_co_u32_e64 v24, s[20:21], 0, v24, vcc
	v_addc_co_u32_e64 v24, s[20:21], 0, v24, s[98:99]
	v_addc_co_u32_e64 v24, s[20:21], 0, v24, s[100:101]
	v_cvt_f32_u32_e32 v24, v24
	s_nop 1
	v_add_f32_dpp v24, v24, v24 quad_perm:[1,0,3,2] row_mask:0xf bank_mask:0xf bound_ctrl:1
	s_nop 1
	v_add_f32_dpp v24, v24, v24 quad_perm:[2,3,0,1] row_mask:0xf bank_mask:0xf bound_ctrl:1
	s_nop 1
	v_add_f32_dpp v24, v24, v24 row_half_mirror row_mask:0xf bank_mask:0xf bound_ctrl:1
	s_nop 1
	v_add_f32_dpp v24, v24, v24 row_mirror row_mask:0xf bank_mask:0xf bound_ctrl:1
	s_nop 0
	v_readlane_b32 s98, v24, 16
	v_readlane_b32 s99, v24, 32
	v_readlane_b32 s100, v24, 48
	s_nop 1
	v_add_f32_e32 v24, s98, v24
	v_add_f32_e32 v24, s99, v24
	v_mov_b32_e32 v25, s100
	s_and_saveexec_b64 s[20:21], s[0:1]
	s_cbranch_execz .LBB0_2712
	s_lshl_b32 s43, s59, 2
	s_add_i32 s43, s42, s43
	s_waitcnt lgkmcnt(0)
	v_add_f32_e32 v24, v24, v25
	v_mov_b32_e32 v25, s43
	ds_write_b32 v25, v24 offset:64
